# residual (mode-2) GEMM epilogue rewritten by hand: residual loads three row groups ahead with counted vmcnt waits, SGPR-base addressing
# baseline (speedup 1.0000x reference)
.LBB0_220:
	s_and_b64 vcc, exec, s[0:1]
	s_cbranch_vccz .LBB0_222
	v_lshl_or_b32 v128, s18, 8, v238
	s_ashr_i32 s0, s19, 5
	v_lshlrev_b32_e32 v176, 2, v128
	s_mul_i32 s0, s0, 0x9000
	s_add_u32 s0, s42, s0
	s_addc_u32 s1, s43, 0
	v_lshl_add_u32 v214, v196, 12, v176
	global_load_dwordx4 v[198:201], v176, s[0:1]
	global_load_dwordx4 v[202:205], v176, s[0:1] offset:16
	global_load_dwordx4 v[206:209], v176, s[0:1] offset:512
	global_load_dwordx4 v[210:213], v176, s[0:1] offset:528
	global_load_dwordx4 v[128:131], v214, s[92:93]
	global_load_dwordx4 v[132:135], v214, s[92:93] offset:16
	global_load_dwordx4 v[136:139], v214, s[92:93] offset:512
	global_load_dwordx4 v[140:143], v214, s[92:93] offset:528
	v_add_u32_e32 v215, 0x10000, v214
	global_load_dwordx4 v[144:147], v215, s[92:93]
	global_load_dwordx4 v[148:151], v215, s[92:93] offset:16
	global_load_dwordx4 v[152:155], v215, s[92:93] offset:512
	global_load_dwordx4 v[156:159], v215, s[92:93] offset:528
	v_add_u32_e32 v216, 0x20000, v214
	global_load_dwordx4 v[160:163], v216, s[92:93]
	global_load_dwordx4 v[164:167], v216, s[92:93] offset:16
	global_load_dwordx4 v[168:171], v216, s[92:93] offset:512
	global_load_dwordx4 v[172:175], v216, s[92:93] offset:528
	v_add_u32_e32 v217, 0x30000, v214
	v_add_u32_e32 v218, 0x80000, v214
	v_add_u32_e32 v219, 0x90000, v214
	v_add_u32_e32 v220, 0xa0000, v214
	v_add_u32_e32 v221, 0xb0000, v214
	s_waitcnt vmcnt(8)
	v_pk_mul_f32 v[198:199], v[198:199], s[94:95]
	v_pk_mul_f32 v[200:201], v[200:201], s[94:95]
	v_pk_mul_f32 v[202:203], v[202:203], s[94:95]
	v_pk_mul_f32 v[204:205], v[204:205], s[94:95]
	v_pk_mul_f32 v[206:207], v[206:207], s[94:95]
	v_pk_mul_f32 v[208:209], v[208:209], s[94:95]
	v_pk_mul_f32 v[210:211], v[210:211], s[94:95]
	v_pk_mul_f32 v[212:213], v[212:213], s[94:95]
	v_pk_fma_f32 v[128:129], v[124:125], v[198:199], v[128:129]
	v_pk_fma_f32 v[130:131], v[126:127], v[200:201], v[130:131]
	v_pk_fma_f32 v[132:133], v[116:117], v[202:203], v[132:133]
	v_pk_fma_f32 v[134:135], v[118:119], v[204:205], v[134:135]
	v_pk_fma_f32 v[136:137], v[120:121], v[206:207], v[136:137]
	v_pk_fma_f32 v[138:139], v[122:123], v[208:209], v[138:139]
	v_pk_fma_f32 v[140:141], v[112:113], v[210:211], v[140:141]
	v_pk_fma_f32 v[142:143], v[114:115], v[212:213], v[142:143]
	global_store_dwordx4 v214, v[128:131], s[90:91]
	global_store_dwordx4 v214, v[132:135], s[90:91] offset:16
	global_store_dwordx4 v214, v[136:139], s[90:91] offset:512
	global_store_dwordx4 v214, v[140:143], s[90:91] offset:528
	global_load_dwordx4 v[112:115], v217, s[92:93]
	global_load_dwordx4 v[116:119], v217, s[92:93] offset:16
	global_load_dwordx4 v[120:123], v217, s[92:93] offset:512
	global_load_dwordx4 v[124:127], v217, s[92:93] offset:528
	s_waitcnt vmcnt(12)
	v_pk_fma_f32 v[144:145], v[108:109], v[198:199], v[144:145]
	v_pk_fma_f32 v[146:147], v[110:111], v[200:201], v[146:147]
	v_pk_fma_f32 v[148:149], v[100:101], v[202:203], v[148:149]
	v_pk_fma_f32 v[150:151], v[102:103], v[204:205], v[150:151]
	v_pk_fma_f32 v[152:153], v[104:105], v[206:207], v[152:153]
	v_pk_fma_f32 v[154:155], v[106:107], v[208:209], v[154:155]
	v_pk_fma_f32 v[156:157], v[96:97], v[210:211], v[156:157]
	v_pk_fma_f32 v[158:159], v[98:99], v[212:213], v[158:159]
	global_store_dwordx4 v215, v[144:147], s[90:91]
	global_store_dwordx4 v215, v[148:151], s[90:91] offset:16
	global_store_dwordx4 v215, v[152:155], s[90:91] offset:512
	global_store_dwordx4 v215, v[156:159], s[90:91] offset:528
	global_load_dwordx4 v[96:99], v218, s[92:93]
	global_load_dwordx4 v[100:103], v218, s[92:93] offset:16
	global_load_dwordx4 v[104:107], v218, s[92:93] offset:512
	global_load_dwordx4 v[108:111], v218, s[92:93] offset:528
	s_waitcnt vmcnt(16)
	v_pk_fma_f32 v[160:161], v[92:93], v[198:199], v[160:161]
	v_pk_fma_f32 v[162:163], v[94:95], v[200:201], v[162:163]
	v_pk_fma_f32 v[164:165], v[84:85], v[202:203], v[164:165]
	v_pk_fma_f32 v[166:167], v[86:87], v[204:205], v[166:167]
	v_pk_fma_f32 v[168:169], v[88:89], v[206:207], v[168:169]
	v_pk_fma_f32 v[170:171], v[90:91], v[208:209], v[170:171]
	v_pk_fma_f32 v[172:173], v[80:81], v[210:211], v[172:173]
	v_pk_fma_f32 v[174:175], v[82:83], v[212:213], v[174:175]
	global_store_dwordx4 v216, v[160:163], s[90:91]
	global_store_dwordx4 v216, v[164:167], s[90:91] offset:16
	global_store_dwordx4 v216, v[168:171], s[90:91] offset:512
	global_store_dwordx4 v216, v[172:175], s[90:91] offset:528
	global_load_dwordx4 v[80:83], v219, s[92:93]
	global_load_dwordx4 v[84:87], v219, s[92:93] offset:16
	global_load_dwordx4 v[88:91], v219, s[92:93] offset:512
	global_load_dwordx4 v[92:95], v219, s[92:93] offset:528
	s_waitcnt vmcnt(16)
	v_pk_fma_f32 v[112:113], v[76:77], v[198:199], v[112:113]
	v_pk_fma_f32 v[114:115], v[78:79], v[200:201], v[114:115]
	v_pk_fma_f32 v[116:117], v[68:69], v[202:203], v[116:117]
	v_pk_fma_f32 v[118:119], v[70:71], v[204:205], v[118:119]
	v_pk_fma_f32 v[120:121], v[72:73], v[206:207], v[120:121]
	v_pk_fma_f32 v[122:123], v[74:75], v[208:209], v[122:123]
	v_pk_fma_f32 v[124:125], v[64:65], v[210:211], v[124:125]
	v_pk_fma_f32 v[126:127], v[66:67], v[212:213], v[126:127]
	global_store_dwordx4 v217, v[112:115], s[90:91]
	global_store_dwordx4 v217, v[116:119], s[90:91] offset:16
	global_store_dwordx4 v217, v[120:123], s[90:91] offset:512
	global_store_dwordx4 v217, v[124:127], s[90:91] offset:528
	global_load_dwordx4 v[64:67], v220, s[92:93]
	global_load_dwordx4 v[68:71], v220, s[92:93] offset:16
	global_load_dwordx4 v[72:75], v220, s[92:93] offset:512
	global_load_dwordx4 v[76:79], v220, s[92:93] offset:528
	s_waitcnt vmcnt(16)
	v_pk_fma_f32 v[96:97], v[60:61], v[198:199], v[96:97]
	v_pk_fma_f32 v[98:99], v[62:63], v[200:201], v[98:99]
	v_pk_fma_f32 v[100:101], v[52:53], v[202:203], v[100:101]
	v_pk_fma_f32 v[102:103], v[54:55], v[204:205], v[102:103]
	v_pk_fma_f32 v[104:105], v[56:57], v[206:207], v[104:105]
	v_pk_fma_f32 v[106:107], v[58:59], v[208:209], v[106:107]
	v_pk_fma_f32 v[108:109], v[48:49], v[210:211], v[108:109]
	v_pk_fma_f32 v[110:111], v[50:51], v[212:213], v[110:111]
	global_store_dwordx4 v218, v[96:99], s[90:91]
	global_store_dwordx4 v218, v[100:103], s[90:91] offset:16
	global_store_dwordx4 v218, v[104:107], s[90:91] offset:512
	global_store_dwordx4 v218, v[108:111], s[90:91] offset:528
	global_load_dwordx4 v[48:51], v221, s[92:93]
	global_load_dwordx4 v[52:55], v221, s[92:93] offset:16
	global_load_dwordx4 v[56:59], v221, s[92:93] offset:512
	global_load_dwordx4 v[60:63], v221, s[92:93] offset:528
	s_waitcnt vmcnt(16)
	v_pk_fma_f32 v[80:81], v[44:45], v[198:199], v[80:81]
	v_pk_fma_f32 v[82:83], v[46:47], v[200:201], v[82:83]
	v_pk_fma_f32 v[84:85], v[36:37], v[202:203], v[84:85]
	v_pk_fma_f32 v[86:87], v[38:39], v[204:205], v[86:87]
	v_pk_fma_f32 v[88:89], v[40:41], v[206:207], v[88:89]
	v_pk_fma_f32 v[90:91], v[42:43], v[208:209], v[90:91]
	v_pk_fma_f32 v[92:93], v[32:33], v[210:211], v[92:93]
	v_pk_fma_f32 v[94:95], v[34:35], v[212:213], v[94:95]
	global_store_dwordx4 v219, v[80:83], s[90:91]
	global_store_dwordx4 v219, v[84:87], s[90:91] offset:16
	global_store_dwordx4 v219, v[88:91], s[90:91] offset:512
	global_store_dwordx4 v219, v[92:95], s[90:91] offset:528
	s_waitcnt vmcnt(12)
	v_pk_fma_f32 v[64:65], v[28:29], v[198:199], v[64:65]
	v_pk_fma_f32 v[66:67], v[30:31], v[200:201], v[66:67]
	v_pk_fma_f32 v[68:69], v[20:21], v[202:203], v[68:69]
	v_pk_fma_f32 v[70:71], v[22:23], v[204:205], v[70:71]
	v_pk_fma_f32 v[72:73], v[24:25], v[206:207], v[72:73]
	v_pk_fma_f32 v[74:75], v[26:27], v[208:209], v[74:75]
	v_pk_fma_f32 v[76:77], v[16:17], v[210:211], v[76:77]
	v_pk_fma_f32 v[78:79], v[18:19], v[212:213], v[78:79]
	global_store_dwordx4 v220, v[64:67], s[90:91]
	global_store_dwordx4 v220, v[68:71], s[90:91] offset:16
	global_store_dwordx4 v220, v[72:75], s[90:91] offset:512
	global_store_dwordx4 v220, v[76:79], s[90:91] offset:528
	s_waitcnt vmcnt(8)
	v_pk_fma_f32 v[48:49], v[12:13], v[198:199], v[48:49]
	v_pk_fma_f32 v[50:51], v[14:15], v[200:201], v[50:51]
	v_pk_fma_f32 v[52:53], v[4:5], v[202:203], v[52:53]
	v_pk_fma_f32 v[54:55], v[6:7], v[204:205], v[54:55]
	v_pk_fma_f32 v[56:57], v[8:9], v[206:207], v[56:57]
	v_pk_fma_f32 v[58:59], v[10:11], v[208:209], v[58:59]
	v_pk_fma_f32 v[60:61], v[0:1], v[210:211], v[60:61]
	v_pk_fma_f32 v[62:63], v[2:3], v[212:213], v[62:63]
	global_store_dwordx4 v221, v[48:51], s[90:91]
	global_store_dwordx4 v221, v[52:55], s[90:91] offset:16
	global_store_dwordx4 v221, v[56:59], s[90:91] offset:512
	global_store_dwordx4 v221, v[60:63], s[90:91] offset:528
